# in-proj unit order: 32 consecutive WG ids = 4 row tiles x 8 column tiles (was 8x4), both layers; on top of deferred queue wait
# speedup vs baseline: 1.0034x; 1.0006x over previous
; __device__ __forceinline__ int opaque_tid(int wave_s) { return (wave_s << 6) | opaque_lane(); }
;     __host__ __device__ bool next(int i, Unit& u) const {
;     ...
;         int wgid = ex ? 0 : L; { const int q = nwg / NXCD, r = nwg % NXCD, xcd = wgid % NXCD, off = wgid / NXCD; wgid = (xcd < r ? xcd * (q + 1) : r * (q + 1) + (xcd - r) * q) + off; }
;         const int nig = WGM * nN, gid = wgid / nig, fm = gid * WGM, gsz = (nM - fm) < WGM ? (nM - fm) : WGM;
;         int pm_m = fm + ((wgid % nig) % gsz), pn_m = (wgid % nig) / gsz;
;         if (nN == 16 && G == 256) {
;             const int xcd = c & 7, j = c >> 3; pm_m = 8 * (2 * i + (xcd >> 2)) + (j & 7); pn_m = 4 * (xcd & 3) + (j >> 3); }
;         if (nN == 64 && G == 256) {
;             const int xcd = c & 7, j = c >> 3; pm_m = 4 * i + (j & 3); pn_m = 8 * xcd + (j >> 2); }
;         const int nk_e = nt / split;
;         u.pm = ex ? 96 : pm_m; u.pn = ex ? e / split : pn_m; u.nkt = ex ? nk_e : nt; u.kt0 = ex ? (e % split) * nk_e : 0;
; template <class Epi, class Sched, bool ALIGN_EPI = false, bool SP2 = false>
; __device__ __forceinline__ void gemm_phase(PG8_LAS unsigned char* lds, const Gemm g, const Sched& S, const Epi& E, int wave_s) {
;     const int tid = opaque_tid(wave_s), wid = __builtin_amdgcn_readfirstlane(tid >> 6), lane = tid & 63, wr = wid >> 2, wc = wid & 3, fr = lane & 15, fq = lane >> 4;
;     const int K = g.K;
;     unsigned voffA[2], voffB[2];
; #pragma unroll
;     for (int i = 0; i < 2; ++i) { int R, C; stage_rc(tid * 16 + i * 8192, R, C); const int Rb = Epi::PERM ? ((R & ~31) + perm32(R & 31)) : R;
;         voffA[i] = (unsigned)(R * K + C) * 2u; voffB[i] = (unsigned)(Rb * K + C) * 2u; }
;     const size_t kstep = (size_t)(BK * 2);
;     const size_t hstep = (size_t)HALF * K * 2;
;     const size_t tstep = 2 * hstep;
;     const unsigned ldsw = (unsigned)wid * 1024u;
;     const int aoff = lds_byte(wr * 64 + fr, fq * 8), boff = lds_byte(wc * 32 + fr, fq * 8);
;     ...
;     Unit cur, nxt; int ui = 0;
;     if (!S.next(0, cur)) return;
;     f32x4 acc[2][2][4][2];
; #pragma unroll
;     for (int a = 0; a < 2; ++a)
; #pragma unroll
;         for (int b = 0; b < 2; ++b)
; #pragma unroll
;             for (int m = 0; m < 4; ++m)
; #pragma unroll
;                 for (int n = 0; n < 2; ++n) acc[a][b][m][n] = (f32x4){0.f, 0.f, 0.f, 0.f};
;     bf16x8 At[4][2], B0[2][2], B1[2][2];
.LBB0_28:
	s_cmp_gt_i32 s68, 2
	s_cbranch_scc1 .LBB0_194
	s_load_dword s3, s[0:1], 0xac
	s_waitcnt lgkmcnt(0)
	s_cmp_lt_i32 s3, 3
	s_cbranch_scc1 .LBB0_194
	s_mov_b64 s[4:5], s[0:1]
	v_mbcnt_lo_u32_b32 v8, -1, 0
	v_mbcnt_hi_u32_b32 v8, -1, v8
	s_cmpk_gt_i32 s2, 0xf88
	v_or_b32_e32 v0, s92, v8
	s_nop 0
	v_readfirstlane_b32 s14, v0
	s_cbranch_scc1 .LBB0_136
	s_cmpk_lt_i32 s2, 0xf60
	s_cselect_b32 s6, s2, 0
	s_ashr_i32 s7, s6, 31
	s_lshr_b32 s7, s7, 29
	s_add_i32 s7, s6, s7
	s_ashr_i32 s8, s7, 3
	s_and_b32 s7, s7, -8
	s_sub_i32 s6, s6, s7
	s_cmp_lt_i32 s6, 0
	s_movk_i32 s33, 0x1ed
	s_cselect_b32 s7, s33, 0x1ec
	s_mul_i32 s6, s6, s7
	s_add_i32 s6, s6, s8
	v_lshlrev_b32_e32 v1, 4, v0
	s_mul_hi_u32 s7, s6, 0x18f9c19
	s_mul_i32 s8, s7, 0xa4
	s_sub_i32 s6, s6, s8
	s_lshl_b32 s7, s7, 2
	s_and_b32 s8, s6, 3
	s_add_i32 s7, s7, s8
	v_add_u32_e32 v2, 0x2000, v1
	v_ashrrev_i32_e32 v3, 31, v2
	v_lshrrev_b32_e32 v3, 22, v3
	v_add_u32_e32 v3, v2, v3
	v_ashrrev_i32_e32 v9, 10, v3
	v_mul_i32_i24_e32 v3, 0x400, v9
	v_sub_u32_e32 v2, v2, v3
	v_lshrrev_b32_e32 v3, 4, v2
	v_bitop3_b32 v2, v3, v2, 32 bitop3:0x6c
	v_ashrrev_i32_e32 v3, 31, v2
	v_lshrrev_b32_e32 v3, 26, v3
	s_cmpk_lt_i32 s2, 0xf60
	v_add_u32_e32 v3, v2, v3
	v_lshlrev_b32_e32 v4, 3, v9
	s_cselect_b32 s44, s7, 0x60
	s_load_dwordx2 s[18:19], s[4:5], 0xa0
	s_add_i32 s4, s2, 0xfffff0a0
	s_lshr_b32 s5, s6, 2
	v_ashrrev_i32_e32 v10, 6, v3
	v_and_b32_e32 v4, -16, v4
	s_cmpk_lt_i32 s2, 0xf60
	v_add_u32_e32 v4, v10, v4
	s_cselect_b32 s42, s5, s4
	v_and_b32_e32 v5, 3, v10
	s_mov_b32 s4, 0x7ffe0
	v_lshrrev_b32_e32 v6, 2, v4
	v_lshlrev_b32_e32 v7, 1, v4
	v_and_b32_e32 v3, 0xc0, v3
	v_and_or_b32 v5, v4, s4, v5
	v_and_b32_e32 v6, 4, v6
	v_and_b32_e32 v7, 24, v7
	v_sub_u32_e32 v2, v2, v3
	v_mov_b32_e32 v3, 1
	v_or3_b32 v5, v5, v6, v7
	v_lshlrev_b32_e32 v6, 5, v9
	v_ashrrev_i16_sdwa v2, v3, sext(v2) dst_sel:DWORD dst_unused:UNUSED_PAD src0_sel:DWORD src1_sel:BYTE_0
	v_and_b32_e32 v6, 32, v6
	v_bfe_i32 v11, v2, 0, 16
	v_add_lshl_u32 v2, v6, v11, 1
	v_lshl_add_u32 v128, v5, 13, v2
	v_lshl_add_u32 v130, v4, 13, v2
	v_bfe_i32 v2, v0, 27, 1
	v_lshrrev_b32_e32 v2, 22, v2
	v_add_u32_e32 v2, v1, v2
	v_and_b32_e32 v2, 0xfffffc00, v2
	v_sub_u32_e32 v1, v1, v2
	v_lshrrev_b32_e32 v2, 4, v1
	v_ashrrev_i32_e32 v4, 31, v0
	v_bitop3_b32 v1, v2, v1, 32 bitop3:0x6c
	v_lshrrev_b32_e32 v4, 26, v4
	v_ashrrev_i32_e32 v2, 31, v1
	v_add_u32_e32 v0, v0, v4
	s_waitcnt lgkmcnt(0)
	s_add_u32 s52, s18, 0x3b200000
	v_lshrrev_b32_e32 v2, 26, v2
	v_ashrrev_i32_e32 v13, 6, v0
	s_addc_u32 s53, s19, 0
	v_add_u32_e32 v2, v1, v2
	v_lshlrev_b32_e32 v0, 3, v13
	s_add_u32 s54, s18, 0x800000
	v_ashrrev_i32_e32 v12, 6, v2
	v_and_b32_e32 v0, -16, v0
	s_addc_u32 s55, s19, 0
	s_ashr_i32 s12, s14, 6
	v_add_u32_e32 v0, v12, v0
	v_and_b32_e32 v4, 3, v12
	s_ashr_i32 s45, s44, 31
	s_ashr_i32 s10, s14, 8
	s_lshl_b32 s56, s12, 10
	v_and_or_b32 v4, v0, s4, v4
	s_lshl_b64 s[4:5], s[44:45], 21
	v_lshrrev_b32_e32 v5, 2, v0
	v_lshlrev_b32_e32 v6, 1, v0
	v_and_b32_e32 v2, 0xc0, v2
	s_add_u32 s46, s52, s4
	v_and_b32_e32 v5, 4, v5
	v_and_b32_e32 v6, 24, v6
	v_sub_u32_e32 v1, v1, v2
	s_addc_u32 s47, s53, s5
	s_ashr_i32 s43, s42, 31
	v_or3_b32 v4, v4, v5, v6
	v_lshlrev_b32_e32 v5, 5, v13
	v_ashrrev_i16_sdwa v1, v3, sext(v1) dst_sel:DWORD dst_unused:UNUSED_PAD src0_sel:DWORD src1_sel:BYTE_0
	s_lshl_b64 s[4:5], s[42:43], 21
	v_and_b32_e32 v5, 32, v5
	v_bfe_i32 v14, v1, 0, 16
	s_add_u32 s48, s54, s4
	v_add_lshl_u32 v1, v5, v14, 1
	s_addc_u32 s49, s55, s5
	s_add_i32 s43, s56, 0
	v_lshl_add_u32 v132, v4, 13, v1
	s_add_i32 m0, s43, 0x10000
	v_lshl_add_u32 v134, v0, 13, v1
	global_load_lds_dwordx4 v132, s[48:49]
	s_add_i32 m0, s43, 0x12000
	s_add_u32 s4, s48, 0x100000
	global_load_lds_dwordx4 v128, s[48:49]
	s_addc_u32 s5, s49, 0
	s_add_i32 m0, s43, 0x14000
	s_add_i32 s57, s43, 0x2000
	global_load_lds_dwordx4 v132, s[4:5]
	s_add_i32 m0, s43, 0x16000
	s_load_dword s60, s[0:1], 0xb0
	global_load_lds_dwordx4 v128, s[4:5]
	s_mov_b32 m0, s43
	s_add_u32 s4, s46, 0x100000
	global_load_lds_dwordx4 v134, s[46:47]
	s_mov_b32 m0, s57
	s_addc_u32 s5, s47, 0
	s_add_i32 s58, s43, 0x4000
	global_load_lds_dwordx4 v130, s[46:47]
	s_mov_b32 m0, s58
	s_add_i32 s59, s43, 0x6000
	global_load_lds_dwordx4 v134, s[4:5]
	s_mov_b32 m0, s59
	v_mov_b32_e32 v133, 0
	global_load_lds_dwordx4 v130, s[4:5]
	v_mov_b32_e32 v129, v133
	v_mov_b32_e32 v135, v133
	v_mov_b32_e32 v131, v133
	s_cmp_eq_u32 s10, 1
	s_mov_b32 s31, 0
	v_lshl_add_u64 v[6:7], s[48:49], 0, v[132:133]
	v_lshl_add_u64 v[4:5], s[48:49], 0, v[128:129]
	v_lshl_add_u64 v[2:3], s[46:47], 0, v[134:135]
	v_lshl_add_u64 v[0:1], s[46:47], 0, v[130:131]
	s_cselect_b64 s[4:5], -1, 0
	s_cmp_lg_u32 s10, 1
	s_movk_i32 s61, 0x4000
	s_cbranch_scc1 .LBB0_33
	s_barrier

;     __host__ __device__ bool next(int i, Unit& u) const {
;         const int L = i * G + c;
;         if (L >= nwg + nN * split) return false;
;         const bool ex = L >= nwg;
;         const int e = ex ? L - nwg : 0;
;         int wgid = ex ? 0 : L; { const int q = nwg / NXCD, r = nwg % NXCD, xcd = wgid % NXCD, off = wgid / NXCD; wgid = (xcd < r ? xcd * (q + 1) : r * (q + 1) + (xcd - r) * q) + off; }
;         const int nig = WGM * nN, gid = wgid / nig, fm = gid * WGM, gsz = (nM - fm) < WGM ? (nM - fm) : WGM;
;         int pm_m = fm + ((wgid % nig) % gsz), pn_m = (wgid % nig) / gsz;
;         if (nN == 16 && G == 256) {
;             const int xcd = c & 7, j = c >> 3; pm_m = 8 * (2 * i + (xcd >> 2)) + (j & 7); pn_m = 4 * (xcd & 3) + (j >> 3); }
;         if (nN == 64 && G == 256) {
;             const int xcd = c & 7, j = c >> 3; pm_m = 4 * i + (j & 3); pn_m = 8 * xcd + (j >> 2); }
;         const int nk_e = nt / split;
;         u.pm = ex ? 96 : pm_m; u.pn = ex ? e / split : pn_m; u.nkt = ex ? nk_e : nt; u.kt0 = ex ? (e % split) * nk_e : 0;
.LBB0_36:
	s_add_i32 s71, s31, 1
	s_waitcnt lgkmcnt(0)
	s_mul_i32 s35, s71, s60
	s_add_i32 s35, s35, s2
	s_cmpk_lt_i32 s35, 0xf89
	s_cselect_b64 s[36:37], -1, 0
	s_cmpk_gt_i32 s35, 0xf88
	s_cbranch_scc1 .LBB0_38
	s_cmpk_lt_i32 s35, 0xf60
	s_cselect_b32 s30, s35, 0
	s_ashr_i32 s34, s30, 31
	s_lshr_b32 s34, s34, 29
	s_add_i32 s34, s30, s34
	s_ashr_i32 s38, s34, 3
	s_and_b32 s34, s34, -8
	s_sub_i32 s30, s30, s34
	s_cmp_lt_i32 s30, 0
	s_cselect_b32 s34, s33, 0x1ec
	s_mul_i32 s30, s30, s34
	s_add_i32 s30, s30, s38
	s_mul_hi_u32 s34, s30, 0x18f9c19
	s_lshl_b32 s40, s34, 2
	s_mulk_i32 s34, 0xa4
	s_sub_i32 s30, s30, s34
	s_lshr_b32 s34, s30, 2
	s_and_b32 s30, s30, 3
	s_add_i32 s40, s40, s30
	s_cmpk_lt_i32 s35, 0xf60
	s_cselect_b32 s30, s40, 0x60
	s_add_i32 s38, s35, 0xfffff0a0
	s_cmpk_lt_i32 s35, 0xf60
	s_sext_i32_i16 s34, s34
	s_cselect_b32 s34, s34, s38

; __device__ __forceinline__ int opaque_tid(int wave_s) { return (wave_s << 6) | opaque_lane(); }
;     __host__ __device__ bool next(int i, Unit& u) const {
;     ...
;         int wgid = ex ? 0 : L; { const int q = nwg / NXCD, r = nwg % NXCD, xcd = wgid % NXCD, off = wgid / NXCD; wgid = (xcd < r ? xcd * (q + 1) : r * (q + 1) + (xcd - r) * q) + off; }
;         const int nig = WGM * nN, gid = wgid / nig, fm = gid * WGM, gsz = (nM - fm) < WGM ? (nM - fm) : WGM;
;         int pm_m = fm + ((wgid % nig) % gsz), pn_m = (wgid % nig) / gsz;
;         if (nN == 16 && G == 256) {
;             const int xcd = c & 7, j = c >> 3; pm_m = 8 * (2 * i + (xcd >> 2)) + (j & 7); pn_m = 4 * (xcd & 3) + (j >> 3); }
;         if (nN == 64 && G == 256) {
;             const int xcd = c & 7, j = c >> 3; pm_m = 4 * i + (j & 3); pn_m = 8 * xcd + (j >> 2); }
;         const int nk_e = nt / split;
;         u.pm = ex ? 96 : pm_m; u.pn = ex ? e / split : pn_m; u.nkt = ex ? nk_e : nt; u.kt0 = ex ? (e % split) * nk_e : 0;
; template <class Epi, class Sched, bool ALIGN_EPI = false, bool SP2 = false>
; __device__ __forceinline__ void gemm_phase(PG8_LAS unsigned char* lds, const Gemm g, const Sched& S, const Epi& E, int wave_s) {
;     const int tid = opaque_tid(wave_s), wid = __builtin_amdgcn_readfirstlane(tid >> 6), lane = tid & 63, wr = wid >> 2, wc = wid & 3, fr = lane & 15, fq = lane >> 4;
;     const int K = g.K;
;     unsigned voffA[2], voffB[2];
; #pragma unroll
;     for (int i = 0; i < 2; ++i) { int R, C; stage_rc(tid * 16 + i * 8192, R, C); const int Rb = Epi::PERM ? ((R & ~31) + perm32(R & 31)) : R;
;         voffA[i] = (unsigned)(R * K + C) * 2u; voffB[i] = (unsigned)(Rb * K + C) * 2u; }
;     const size_t kstep = (size_t)(BK * 2);
;     const size_t hstep = (size_t)HALF * K * 2;
;     const size_t tstep = 2 * hstep;
;     const unsigned ldsw = (unsigned)wid * 1024u;
;     const int aoff = lds_byte(wr * 64 + fr, fq * 8), boff = lds_byte(wc * 32 + fr, fq * 8);
;     ...
;     Unit cur, nxt; int ui = 0;
;     if (!S.next(0, cur)) return;
;     f32x4 acc[2][2][4][2];
; #pragma unroll
;     for (int a = 0; a < 2; ++a)
; #pragma unroll
;         for (int b = 0; b < 2; ++b)
; #pragma unroll
;             for (int m = 0; m < 4; ++m)
; #pragma unroll
;                 for (int n = 0; n < 2; ++n) acc[a][b][m][n] = (f32x4){0.f, 0.f, 0.f, 0.f};
;     bf16x8 At[4][2], B0[2][2], B1[2][2];
.LBB0_1540:
	s_cmp_gt_i32 s68, 12
	s_cbranch_scc1 .LBB0_1607
	s_load_dword s3, s[0:1], 0xac
	s_waitcnt lgkmcnt(0)
	s_cmp_lt_i32 s3, 13
	s_cbranch_scc1 .LBB0_1607
	s_mov_b64 s[4:5], s[0:1]
	v_mbcnt_lo_u32_b32 v8, -1, 0
	v_mbcnt_hi_u32_b32 v8, -1, v8
	s_cmpk_gt_i32 s2, 0xf88
	v_or_b32_e32 v0, s92, v8
	s_nop 0
	v_readfirstlane_b32 s14, v0
	s_cbranch_scc1 .LBB0_1566
	s_cmpk_lt_i32 s2, 0xf60
	s_cselect_b32 s6, s2, 0
	s_ashr_i32 s7, s6, 31
	s_lshr_b32 s7, s7, 29
	s_add_i32 s7, s6, s7
	s_ashr_i32 s8, s7, 3
	s_and_b32 s7, s7, -8
	s_sub_i32 s6, s6, s7
	s_cmp_lt_i32 s6, 0
	s_movk_i32 s33, 0x1ed
	s_cselect_b32 s7, s33, 0x1ec
	s_mul_i32 s6, s6, s7
	s_add_i32 s6, s6, s8
	v_lshlrev_b32_e32 v1, 4, v0
	s_mul_hi_u32 s7, s6, 0x18f9c19
	s_mul_i32 s8, s7, 0xa4
	s_sub_i32 s6, s6, s8
	s_lshl_b32 s7, s7, 2
	s_and_b32 s8, s6, 3
	s_add_i32 s7, s7, s8
	v_add_u32_e32 v2, 0x2000, v1
	v_ashrrev_i32_e32 v3, 31, v2
	v_lshrrev_b32_e32 v3, 22, v3
	v_add_u32_e32 v3, v2, v3
	v_ashrrev_i32_e32 v9, 10, v3
	v_mul_i32_i24_e32 v3, 0x400, v9
	v_sub_u32_e32 v2, v2, v3
	v_lshrrev_b32_e32 v3, 4, v2
	v_bitop3_b32 v2, v3, v2, 32 bitop3:0x6c
	v_ashrrev_i32_e32 v3, 31, v2
	v_lshrrev_b32_e32 v3, 26, v3
	s_cmpk_lt_i32 s2, 0xf60
	v_add_u32_e32 v3, v2, v3
	v_lshlrev_b32_e32 v4, 3, v9
	s_cselect_b32 s44, s7, 0x60
	s_load_dwordx2 s[18:19], s[4:5], 0xa0
	s_add_i32 s4, s2, 0xfffff0a0
	s_lshr_b32 s5, s6, 2
	v_ashrrev_i32_e32 v10, 6, v3
	v_and_b32_e32 v4, -16, v4
	s_cmpk_lt_i32 s2, 0xf60
	v_add_u32_e32 v4, v10, v4
	s_cselect_b32 s42, s5, s4
	v_and_b32_e32 v5, 3, v10
	s_mov_b32 s4, 0x7ffe0
	v_lshrrev_b32_e32 v6, 2, v4
	v_lshlrev_b32_e32 v7, 1, v4
	v_and_b32_e32 v3, 0xc0, v3
	v_and_or_b32 v5, v4, s4, v5
	v_and_b32_e32 v6, 4, v6
	v_and_b32_e32 v7, 24, v7
	v_sub_u32_e32 v2, v2, v3
	v_mov_b32_e32 v3, 1
	v_or3_b32 v5, v5, v6, v7
	v_lshlrev_b32_e32 v6, 5, v9
	v_ashrrev_i16_sdwa v2, v3, sext(v2) dst_sel:DWORD dst_unused:UNUSED_PAD src0_sel:DWORD src1_sel:BYTE_0
	v_and_b32_e32 v6, 32, v6
	v_bfe_i32 v11, v2, 0, 16
	v_add_lshl_u32 v2, v6, v11, 1
	v_lshl_add_u32 v128, v5, 13, v2
	v_lshl_add_u32 v130, v4, 13, v2
	v_bfe_i32 v2, v0, 27, 1
	v_lshrrev_b32_e32 v2, 22, v2
	v_add_u32_e32 v2, v1, v2
	v_and_b32_e32 v2, 0xfffffc00, v2
	v_sub_u32_e32 v1, v1, v2
	v_lshrrev_b32_e32 v2, 4, v1
	v_ashrrev_i32_e32 v4, 31, v0
	v_bitop3_b32 v1, v2, v1, 32 bitop3:0x6c
	v_lshrrev_b32_e32 v4, 26, v4
	v_ashrrev_i32_e32 v2, 31, v1
	v_add_u32_e32 v0, v0, v4
	s_waitcnt lgkmcnt(0)
	s_add_u32 s52, s18, 0x3b200000
	v_lshrrev_b32_e32 v2, 26, v2
	s_waitcnt vmcnt(0)
	v_ashrrev_i32_e32 v13, 6, v0
	s_addc_u32 s53, s19, 0
	v_add_u32_e32 v2, v1, v2
	v_lshlrev_b32_e32 v0, 3, v13
	s_add_u32 s54, s18, 0x5a00000
	v_ashrrev_i32_e32 v12, 6, v2
	v_and_b32_e32 v0, -16, v0
	s_addc_u32 s55, s19, 0
	s_ashr_i32 s12, s14, 6
	v_add_u32_e32 v0, v12, v0
	v_and_b32_e32 v4, 3, v12
	s_ashr_i32 s45, s44, 31
	s_ashr_i32 s10, s14, 8
	s_lshl_b32 s56, s12, 10
	v_and_or_b32 v4, v0, s4, v4
	s_lshl_b64 s[4:5], s[44:45], 21
	v_lshrrev_b32_e32 v5, 2, v0
	v_lshlrev_b32_e32 v6, 1, v0
	v_and_b32_e32 v2, 0xc0, v2
	s_add_u32 s46, s52, s4
	v_and_b32_e32 v5, 4, v5
	v_and_b32_e32 v6, 24, v6
	v_sub_u32_e32 v1, v1, v2
	s_addc_u32 s47, s53, s5
	s_ashr_i32 s43, s42, 31
	v_or3_b32 v4, v4, v5, v6
	v_lshlrev_b32_e32 v5, 5, v13
	v_ashrrev_i16_sdwa v1, v3, sext(v1) dst_sel:DWORD dst_unused:UNUSED_PAD src0_sel:DWORD src1_sel:BYTE_0
	s_lshl_b64 s[4:5], s[42:43], 21
	v_and_b32_e32 v5, 32, v5
	v_bfe_i32 v14, v1, 0, 16
	s_add_u32 s48, s54, s4
	v_add_lshl_u32 v1, v5, v14, 1
	s_addc_u32 s49, s55, s5
	s_add_i32 s43, s56, 0
	v_lshl_add_u32 v132, v4, 13, v1
	s_add_i32 m0, s43, 0x10000
	v_lshl_add_u32 v134, v0, 13, v1
	global_load_lds_dwordx4 v132, s[48:49]
	s_add_i32 m0, s43, 0x12000
	s_add_u32 s4, s48, 0x100000
	global_load_lds_dwordx4 v128, s[48:49]
	s_addc_u32 s5, s49, 0
	s_add_i32 m0, s43, 0x14000
	s_add_i32 s57, s43, 0x2000
	global_load_lds_dwordx4 v132, s[4:5]
	s_add_i32 m0, s43, 0x16000
	s_load_dword s60, s[0:1], 0xb0
	global_load_lds_dwordx4 v128, s[4:5]
	s_mov_b32 m0, s43
	s_add_u32 s4, s46, 0x100000
	global_load_lds_dwordx4 v134, s[46:47]
	s_mov_b32 m0, s57
	s_addc_u32 s5, s47, 0
	s_add_i32 s58, s43, 0x4000
	global_load_lds_dwordx4 v130, s[46:47]
	s_mov_b32 m0, s58
	s_add_i32 s59, s43, 0x6000
	global_load_lds_dwordx4 v134, s[4:5]
	s_mov_b32 m0, s59
	v_mov_b32_e32 v133, 0
	global_load_lds_dwordx4 v130, s[4:5]
	v_mov_b32_e32 v129, v133
	v_mov_b32_e32 v135, v133
	v_mov_b32_e32 v131, v133
	s_cmp_eq_u32 s10, 1
	s_mov_b32 s31, 0
	v_lshl_add_u64 v[6:7], s[48:49], 0, v[132:133]
	v_lshl_add_u64 v[4:5], s[48:49], 0, v[128:129]
	v_lshl_add_u64 v[2:3], s[46:47], 0, v[134:135]
	v_lshl_add_u64 v[0:1], s[46:47], 0, v[130:131]
	s_cselect_b64 s[4:5], -1, 0
	s_cmp_lg_u32 s10, 1
	s_movk_i32 s61, 0x4000
	s_cbranch_scc1 .LBB0_1545
	s_barrier
